# peel + no redundant fence + per-tile align/stagger barriers removed for QKV and FFN-in GEMMs (epilogue of older half overlaps younger half's last MFMA segment)
# speedup vs baseline: 1.0013x; 1.0013x over previous
.LBB0_497:
	s_and_b64 vcc, exec, s[4:5]
	s_cbranch_vccz .Lnoalign_0
	s_barrier
.Lnoalign_0:
	s_waitcnt vmcnt(0)
	s_mov_b32 s25, 0xf800000
	s_barrier

.LBB0_1571:
	s_and_b64 vcc, exec, s[4:5]
	s_cbranch_vccz .Lnoalign_4
	s_barrier
.Lnoalign_4:
	s_waitcnt vmcnt(0)
	s_barrier
